# attention epilogues rewritten (diff + stick-breaking): per-row rmsnorm via reduce-scatter butterfly, one exact rsqrt per lane, LDS all-gather, packed f32 mults; on top of row loops + tr_item burst + w
# speedup vs baseline: 1.0072x; 1.0063x over previous
; __device__ __forceinline__ float bf_lo(unsigned u) { return __uint_as_float(u << 16); }
; __device__ __forceinline__ float bf_hi(unsigned u) { return __uint_as_float(u & 0xffff0000u); }
; __device__ __forceinline__ void diff_unit(const Params& p, LAS unsigned char* lds, int b, int h, int qb, float lam) {
;     ...
;         for (int r = 0; r < 16; ++r) { const float a = (mp == 0 ? 1.0f : lam) / L[r];
; #pragma unroll
;             for (int db = 0; db < 4; ++db) O[db][r] *= a; }
;     ...
;         for (int db = 0; db < 4; ++db) { const unsigned w = park[(db * 8 + (r >> 1)) * 64]; o[db] = ((r & 1) ? bf_hi(w) : bf_lo(w)) - O[db][r]; ss += o[db] * o[db]; }
.LBB0_267:
	s_nop 11
	s_waitcnt vmcnt(0)
	s_barrier
	s_mov_b64 s[0:1], 0x1000
	v_lshl_add_u64 v[14:15], v[164:165], 0, s[0:1]
	global_load_dword v136, v[164:165], off
	global_load_dword v137, v[164:165], off offset:256
	global_load_dword v138, v[164:165], off offset:512
	global_load_dword v139, v[164:165], off offset:768
	global_load_dword v140, v[164:165], off offset:1024
	global_load_dword v141, v[164:165], off offset:1280
	global_load_dword v142, v[164:165], off offset:1536
	global_load_dword v143, v[164:165], off offset:1792
	global_load_dword v144, v[164:165], off offset:2048
	global_load_dword v145, v[164:165], off offset:2304
	global_load_dword v146, v[164:165], off offset:2560
	global_load_dword v147, v[164:165], off offset:2816
	global_load_dword v148, v[164:165], off offset:3072
	global_load_dword v149, v[164:165], off offset:3328
	global_load_dword v150, v[164:165], off offset:3584
	global_load_dword v151, v[164:165], off offset:3840
	global_load_dword v152, v[14:15], off
	global_load_dword v153, v[14:15], off offset:256
	global_load_dword v154, v[14:15], off offset:512
	global_load_dword v155, v[14:15], off offset:768
	global_load_dword v156, v[14:15], off offset:1024
	global_load_dword v157, v[14:15], off offset:1280
	global_load_dword v158, v[14:15], off offset:1536
	global_load_dword v159, v[14:15], off offset:1792
	global_load_dword v176, v[14:15], off offset:2048
	global_load_dword v177, v[14:15], off offset:2304
	global_load_dword v178, v[14:15], off offset:2560
	global_load_dword v179, v[14:15], off offset:2816
	global_load_dword v180, v[14:15], off offset:3072
	global_load_dword v181, v[14:15], off offset:3328
	global_load_dword v182, v[14:15], off offset:3584
	global_load_dword v183, v[14:15], off offset:3840
	v_div_scale_f32 v2, s[0:1], v80, v80, v161
	v_rcp_f32_e32 v3, v2
	v_div_scale_f32 v4, vcc, v161, v80, v161
	v_fma_f32 v5, -v2, v3, 1.0
	v_fmac_f32_e32 v3, v5, v3
	v_mul_f32_e32 v5, v4, v3
	v_fma_f32 v6, -v2, v5, v4
	v_fmac_f32_e32 v5, v6, v3
	v_fma_f32 v2, -v2, v5, v4
	v_div_fmas_f32 v2, v2, v3, v5
	v_div_fixup_f32 v112, v2, v80, v161
	v_div_scale_f32 v2, s[0:1], v81, v81, v161
	v_rcp_f32_e32 v3, v2
	v_div_scale_f32 v4, vcc, v161, v81, v161
	v_fma_f32 v5, -v2, v3, 1.0
	v_fmac_f32_e32 v3, v5, v3
	v_mul_f32_e32 v5, v4, v3
	v_fma_f32 v6, -v2, v5, v4
	v_fmac_f32_e32 v5, v6, v3
	v_fma_f32 v2, -v2, v5, v4
	v_div_fmas_f32 v2, v2, v3, v5
	v_div_fixup_f32 v113, v2, v81, v161
	v_div_scale_f32 v2, s[0:1], v82, v82, v161
	v_rcp_f32_e32 v3, v2
	v_div_scale_f32 v4, vcc, v161, v82, v161
	v_fma_f32 v5, -v2, v3, 1.0
	v_fmac_f32_e32 v3, v5, v3
	v_mul_f32_e32 v5, v4, v3
	v_fma_f32 v6, -v2, v5, v4
	v_fmac_f32_e32 v5, v6, v3
	v_fma_f32 v2, -v2, v5, v4
	v_div_fmas_f32 v2, v2, v3, v5
	v_div_fixup_f32 v114, v2, v82, v161
	v_div_scale_f32 v2, s[0:1], v83, v83, v161
	v_rcp_f32_e32 v3, v2
	v_div_scale_f32 v4, vcc, v161, v83, v161
	v_fma_f32 v5, -v2, v3, 1.0
	v_fmac_f32_e32 v3, v5, v3
	v_mul_f32_e32 v5, v4, v3
	v_fma_f32 v6, -v2, v5, v4
	v_fmac_f32_e32 v5, v6, v3
	v_fma_f32 v2, -v2, v5, v4
	v_div_fmas_f32 v2, v2, v3, v5
	v_div_fixup_f32 v115, v2, v83, v161
	v_div_scale_f32 v2, s[0:1], v84, v84, v161
	v_rcp_f32_e32 v3, v2
	v_div_scale_f32 v4, vcc, v161, v84, v161
	v_fma_f32 v5, -v2, v3, 1.0
	v_fmac_f32_e32 v3, v5, v3
	v_mul_f32_e32 v5, v4, v3
	v_fma_f32 v6, -v2, v5, v4
	v_fmac_f32_e32 v5, v6, v3
	v_fma_f32 v2, -v2, v5, v4
	v_div_fmas_f32 v2, v2, v3, v5
	v_div_fixup_f32 v116, v2, v84, v161
	v_div_scale_f32 v2, s[0:1], v85, v85, v161
	v_rcp_f32_e32 v3, v2
	v_div_scale_f32 v4, vcc, v161, v85, v161
	v_fma_f32 v5, -v2, v3, 1.0
	v_fmac_f32_e32 v3, v5, v3
	v_mul_f32_e32 v5, v4, v3
	v_fma_f32 v6, -v2, v5, v4
	v_fmac_f32_e32 v5, v6, v3
	v_fma_f32 v2, -v2, v5, v4
	v_div_fmas_f32 v2, v2, v3, v5
	v_div_fixup_f32 v117, v2, v85, v161
	v_div_scale_f32 v2, s[0:1], v86, v86, v161
	v_rcp_f32_e32 v3, v2
	v_div_scale_f32 v4, vcc, v161, v86, v161
	v_fma_f32 v5, -v2, v3, 1.0
	v_fmac_f32_e32 v3, v5, v3
	v_mul_f32_e32 v5, v4, v3
	v_fma_f32 v6, -v2, v5, v4
	v_fmac_f32_e32 v5, v6, v3
	v_fma_f32 v2, -v2, v5, v4
	v_div_fmas_f32 v2, v2, v3, v5
	v_div_fixup_f32 v118, v2, v86, v161
	v_div_scale_f32 v2, s[0:1], v87, v87, v161
	v_rcp_f32_e32 v3, v2
	v_div_scale_f32 v4, vcc, v161, v87, v161
	v_fma_f32 v5, -v2, v3, 1.0
	v_fmac_f32_e32 v3, v5, v3
	v_mul_f32_e32 v5, v4, v3
	v_fma_f32 v6, -v2, v5, v4
	v_fmac_f32_e32 v5, v6, v3
	v_fma_f32 v2, -v2, v5, v4
	v_div_fmas_f32 v2, v2, v3, v5
	v_div_fixup_f32 v119, v2, v87, v161
	v_div_scale_f32 v2, s[0:1], v88, v88, v161
	v_rcp_f32_e32 v3, v2
	v_div_scale_f32 v4, vcc, v161, v88, v161
	v_fma_f32 v5, -v2, v3, 1.0
	v_fmac_f32_e32 v3, v5, v3
	v_mul_f32_e32 v5, v4, v3
	v_fma_f32 v6, -v2, v5, v4
	v_fmac_f32_e32 v5, v6, v3
	v_fma_f32 v2, -v2, v5, v4
	v_div_fmas_f32 v2, v2, v3, v5
	v_div_fixup_f32 v120, v2, v88, v161
	v_div_scale_f32 v2, s[0:1], v89, v89, v161
	v_rcp_f32_e32 v3, v2
	v_div_scale_f32 v4, vcc, v161, v89, v161
	v_fma_f32 v5, -v2, v3, 1.0
	v_fmac_f32_e32 v3, v5, v3
	v_mul_f32_e32 v5, v4, v3
	v_fma_f32 v6, -v2, v5, v4
	v_fmac_f32_e32 v5, v6, v3
	v_fma_f32 v2, -v2, v5, v4
	v_div_fmas_f32 v2, v2, v3, v5
	v_div_fixup_f32 v121, v2, v89, v161
	v_div_scale_f32 v2, s[0:1], v90, v90, v161
	v_rcp_f32_e32 v3, v2
	v_div_scale_f32 v4, vcc, v161, v90, v161
	v_fma_f32 v5, -v2, v3, 1.0
	v_fmac_f32_e32 v3, v5, v3
	v_mul_f32_e32 v5, v4, v3
	v_fma_f32 v6, -v2, v5, v4
	v_fmac_f32_e32 v5, v6, v3
	v_fma_f32 v2, -v2, v5, v4
	v_div_fmas_f32 v2, v2, v3, v5
	v_div_fixup_f32 v122, v2, v90, v161
	v_div_scale_f32 v2, s[0:1], v91, v91, v161
	v_rcp_f32_e32 v3, v2
	v_div_scale_f32 v4, vcc, v161, v91, v161
	v_fma_f32 v5, -v2, v3, 1.0
	v_fmac_f32_e32 v3, v5, v3
; __device__ __forceinline__ float bf_lo(unsigned u) { return __uint_as_float(u << 16); }
; __device__ __forceinline__ float bf_hi(unsigned u) { return __uint_as_float(u & 0xffff0000u); }
; __device__ __forceinline__ void diff_unit(const Params& p, LAS unsigned char* lds, int b, int h, int qb, float lam) {
;     ...
;         for (int r = 0; r < 16; ++r) { const float a = (mp == 0 ? 1.0f : lam) / L[r];
; #pragma unroll
;             for (int db = 0; db < 4; ++db) O[db][r] *= a; }
;     ...
;         for (int db = 0; db < 4; ++db) { const unsigned w = park[(db * 8 + (r >> 1)) * 64]; o[db] = ((r & 1) ? bf_hi(w) : bf_lo(w)) - O[db][r]; ss += o[db] * o[db]; }
	v_mul_f32_e32 v5, v4, v3
	v_fma_f32 v6, -v2, v5, v4
	v_fmac_f32_e32 v5, v6, v3
	v_fma_f32 v2, -v2, v5, v4
	v_div_fmas_f32 v2, v2, v3, v5
	v_div_fixup_f32 v123, v2, v91, v161
	v_div_scale_f32 v2, s[0:1], v92, v92, v161
	v_rcp_f32_e32 v3, v2
	v_div_scale_f32 v4, vcc, v161, v92, v161
	v_fma_f32 v5, -v2, v3, 1.0
	v_fmac_f32_e32 v3, v5, v3
	v_mul_f32_e32 v5, v4, v3
	v_fma_f32 v6, -v2, v5, v4
	v_fmac_f32_e32 v5, v6, v3
	v_fma_f32 v2, -v2, v5, v4
	v_div_fmas_f32 v2, v2, v3, v5
	v_div_fixup_f32 v124, v2, v92, v161
	v_div_scale_f32 v2, s[0:1], v93, v93, v161
	v_rcp_f32_e32 v3, v2
	v_div_scale_f32 v4, vcc, v161, v93, v161
	v_fma_f32 v5, -v2, v3, 1.0
	v_fmac_f32_e32 v3, v5, v3
	v_mul_f32_e32 v5, v4, v3
	v_fma_f32 v6, -v2, v5, v4
	v_fmac_f32_e32 v5, v6, v3
	v_fma_f32 v2, -v2, v5, v4
	v_div_fmas_f32 v2, v2, v3, v5
	v_div_fixup_f32 v125, v2, v93, v161
	v_div_scale_f32 v2, s[0:1], v94, v94, v161
	v_rcp_f32_e32 v3, v2
	v_div_scale_f32 v4, vcc, v161, v94, v161
	v_fma_f32 v5, -v2, v3, 1.0
	v_fmac_f32_e32 v3, v5, v3
	v_mul_f32_e32 v5, v4, v3
	v_fma_f32 v6, -v2, v5, v4
	v_fmac_f32_e32 v5, v6, v3
	v_fma_f32 v2, -v2, v5, v4
	v_div_fmas_f32 v2, v2, v3, v5
	v_div_fixup_f32 v126, v2, v94, v161
	v_div_scale_f32 v2, s[0:1], v95, v95, v161
	v_rcp_f32_e32 v3, v2
	v_div_scale_f32 v4, vcc, v161, v95, v161
	v_fma_f32 v5, -v2, v3, 1.0
	v_fmac_f32_e32 v3, v5, v3
	v_mul_f32_e32 v5, v4, v3
	v_fma_f32 v6, -v2, v5, v4
	v_fmac_f32_e32 v5, v6, v3
	v_fma_f32 v2, -v2, v5, v4
	v_div_fmas_f32 v2, v2, v3, v5
	v_div_fixup_f32 v127, v2, v95, v161
	s_waitcnt vmcnt(0)
	v_lshlrev_b32_e32 v128, 16, v136
	v_and_b32_e32 v129, 0xffff0000, v136
	v_pk_fma_f32 v[16:17], v[16:17], v[112:113], v[128:129] neg_lo:[1,0,0] neg_hi:[1,0,0]
	v_lshlrev_b32_e32 v130, 16, v137
	v_and_b32_e32 v131, 0xffff0000, v137
	v_pk_fma_f32 v[18:19], v[18:19], v[114:115], v[130:131] neg_lo:[1,0,0] neg_hi:[1,0,0]
	v_lshlrev_b32_e32 v128, 16, v138
	v_and_b32_e32 v129, 0xffff0000, v138
	v_pk_fma_f32 v[20:21], v[20:21], v[116:117], v[128:129] neg_lo:[1,0,0] neg_hi:[1,0,0]
	v_lshlrev_b32_e32 v130, 16, v139
	v_and_b32_e32 v131, 0xffff0000, v139
	v_pk_fma_f32 v[22:23], v[22:23], v[118:119], v[130:131] neg_lo:[1,0,0] neg_hi:[1,0,0]
	v_lshlrev_b32_e32 v128, 16, v140
	v_and_b32_e32 v129, 0xffff0000, v140
	v_pk_fma_f32 v[24:25], v[24:25], v[120:121], v[128:129] neg_lo:[1,0,0] neg_hi:[1,0,0]
	v_lshlrev_b32_e32 v130, 16, v141
	v_and_b32_e32 v131, 0xffff0000, v141
	v_pk_fma_f32 v[26:27], v[26:27], v[122:123], v[130:131] neg_lo:[1,0,0] neg_hi:[1,0,0]
	v_lshlrev_b32_e32 v128, 16, v142
	v_and_b32_e32 v129, 0xffff0000, v142
	v_pk_fma_f32 v[28:29], v[28:29], v[124:125], v[128:129] neg_lo:[1,0,0] neg_hi:[1,0,0]
	v_lshlrev_b32_e32 v130, 16, v143
	v_and_b32_e32 v131, 0xffff0000, v143
	v_pk_fma_f32 v[30:31], v[30:31], v[126:127], v[130:131] neg_lo:[1,0,0] neg_hi:[1,0,0]
	v_lshlrev_b32_e32 v128, 16, v144
	v_and_b32_e32 v129, 0xffff0000, v144
	v_pk_fma_f32 v[32:33], v[32:33], v[112:113], v[128:129] neg_lo:[1,0,0] neg_hi:[1,0,0]
	v_lshlrev_b32_e32 v130, 16, v145
	v_and_b32_e32 v131, 0xffff0000, v145
	v_pk_fma_f32 v[34:35], v[34:35], v[114:115], v[130:131] neg_lo:[1,0,0] neg_hi:[1,0,0]
	v_lshlrev_b32_e32 v128, 16, v146
	v_and_b32_e32 v129, 0xffff0000, v146
	v_pk_fma_f32 v[36:37], v[36:37], v[116:117], v[128:129] neg_lo:[1,0,0] neg_hi:[1,0,0]
	v_lshlrev_b32_e32 v130, 16, v147
	v_and_b32_e32 v131, 0xffff0000, v147
	v_pk_fma_f32 v[38:39], v[38:39], v[118:119], v[130:131] neg_lo:[1,0,0] neg_hi:[1,0,0]
	v_lshlrev_b32_e32 v128, 16, v148
	v_and_b32_e32 v129, 0xffff0000, v148
	v_pk_fma_f32 v[40:41], v[40:41], v[120:121], v[128:129] neg_lo:[1,0,0] neg_hi:[1,0,0]
	v_lshlrev_b32_e32 v130, 16, v149
	v_and_b32_e32 v131, 0xffff0000, v149
	v_pk_fma_f32 v[42:43], v[42:43], v[122:123], v[130:131] neg_lo:[1,0,0] neg_hi:[1,0,0]
	v_lshlrev_b32_e32 v128, 16, v150
	v_and_b32_e32 v129, 0xffff0000, v150
	v_pk_fma_f32 v[44:45], v[44:45], v[124:125], v[128:129] neg_lo:[1,0,0] neg_hi:[1,0,0]
	v_lshlrev_b32_e32 v130, 16, v151
	v_and_b32_e32 v131, 0xffff0000, v151
	v_pk_fma_f32 v[46:47], v[46:47], v[126:127], v[130:131] neg_lo:[1,0,0] neg_hi:[1,0,0]
	v_lshlrev_b32_e32 v128, 16, v152
	v_and_b32_e32 v129, 0xffff0000, v152
	v_pk_fma_f32 v[48:49], v[48:49], v[112:113], v[128:129] neg_lo:[1,0,0] neg_hi:[1,0,0]
	v_lshlrev_b32_e32 v130, 16, v153
	v_and_b32_e32 v131, 0xffff0000, v153
	v_pk_fma_f32 v[50:51], v[50:51], v[114:115], v[130:131] neg_lo:[1,0,0] neg_hi:[1,0,0]
	v_lshlrev_b32_e32 v128, 16, v154
	v_and_b32_e32 v129, 0xffff0000, v154
	v_pk_fma_f32 v[52:53], v[52:53], v[116:117], v[128:129] neg_lo:[1,0,0] neg_hi:[1,0,0]
	v_lshlrev_b32_e32 v130, 16, v155
	v_and_b32_e32 v131, 0xffff0000, v155
	v_pk_fma_f32 v[54:55], v[54:55], v[118:119], v[130:131] neg_lo:[1,0,0] neg_hi:[1,0,0]
	v_lshlrev_b32_e32 v128, 16, v156
	v_and_b32_e32 v129, 0xffff0000, v156
	v_pk_fma_f32 v[56:57], v[56:57], v[120:121], v[128:129] neg_lo:[1,0,0] neg_hi:[1,0,0]
	v_lshlrev_b32_e32 v130, 16, v157
	v_and_b32_e32 v131, 0xffff0000, v157
	v_pk_fma_f32 v[58:59], v[58:59], v[122:123], v[130:131] neg_lo:[1,0,0] neg_hi:[1,0,0]
	v_lshlrev_b32_e32 v128, 16, v158
	v_and_b32_e32 v129, 0xffff0000, v158
	v_pk_fma_f32 v[60:61], v[60:61], v[124:125], v[128:129] neg_lo:[1,0,0] neg_hi:[1,0,0]
	v_lshlrev_b32_e32 v130, 16, v159
	v_and_b32_e32 v131, 0xffff0000, v159
	v_pk_fma_f32 v[62:63], v[62:63], v[126:127], v[130:131] neg_lo:[1,0,0] neg_hi:[1,0,0]
	v_lshlrev_b32_e32 v128, 16, v176
	v_and_b32_e32 v129, 0xffff0000, v176
	v_pk_fma_f32 v[64:65], v[64:65], v[112:113], v[128:129] neg_lo:[1,0,0] neg_hi:[1,0,0]
	v_lshlrev_b32_e32 v130, 16, v177
	v_and_b32_e32 v131, 0xffff0000, v177
	v_pk_fma_f32 v[66:67], v[66:67], v[114:115], v[130:131] neg_lo:[1,0,0] neg_hi:[1,0,0]
; __device__ __forceinline__ float bf_lo(unsigned u) { return __uint_as_float(u << 16); }
; __device__ __forceinline__ float bf_hi(unsigned u) { return __uint_as_float(u & 0xffff0000u); }
; __device__ __forceinline__ int crow(int r, int h) { return (r & 3) + 8 * (r >> 2) + 4 * h; }
; __device__ __forceinline__ void diff_unit(const Params& p, LAS unsigned char* lds, int b, int h, int qb, float lam) {
;     ...
;     for (int db = 0; db < 4; ++db) gn[db] = p.diff_gain[32 * db + c] * 0.8f;
; #pragma unroll
;     for (int r = 0; r < 16; ++r) {
;         const int qr = crow(r, hh);
;         float o[4]; float ss = 0.f;
; #pragma unroll
;         for (int db = 0; db < 4; ++db) { const unsigned w = park[(db * 8 + (r >> 1)) * 64]; o[db] = ((r & 1) ? bf_hi(w) : bf_lo(w)) - O[db][r]; ss += o[db] * o[db]; }
; #pragma unroll
;         for (int off = 1; off < 32; off <<= 1) ss += __shfl_xor(ss, off);
;         const float rs = 1.0f / sqrtf(ss * (1.0f / 128.0f) + EPS);
	v_lshlrev_b32_e32 v128, 16, v178
	v_and_b32_e32 v129, 0xffff0000, v178
	v_pk_fma_f32 v[68:69], v[68:69], v[116:117], v[128:129] neg_lo:[1,0,0] neg_hi:[1,0,0]
	v_lshlrev_b32_e32 v130, 16, v179
	v_and_b32_e32 v131, 0xffff0000, v179
	v_pk_fma_f32 v[70:71], v[70:71], v[118:119], v[130:131] neg_lo:[1,0,0] neg_hi:[1,0,0]
	v_lshlrev_b32_e32 v128, 16, v180
	v_and_b32_e32 v129, 0xffff0000, v180
	v_pk_fma_f32 v[72:73], v[72:73], v[120:121], v[128:129] neg_lo:[1,0,0] neg_hi:[1,0,0]
	v_lshlrev_b32_e32 v130, 16, v181
	v_and_b32_e32 v131, 0xffff0000, v181
	v_pk_fma_f32 v[74:75], v[74:75], v[122:123], v[130:131] neg_lo:[1,0,0] neg_hi:[1,0,0]
	v_lshlrev_b32_e32 v128, 16, v182
	v_and_b32_e32 v129, 0xffff0000, v182
	v_pk_fma_f32 v[76:77], v[76:77], v[124:125], v[128:129] neg_lo:[1,0,0] neg_hi:[1,0,0]
	v_lshlrev_b32_e32 v130, 16, v183
	v_and_b32_e32 v131, 0xffff0000, v183
	v_pk_fma_f32 v[78:79], v[78:79], v[126:127], v[130:131] neg_lo:[1,0,0] neg_hi:[1,0,0]
	v_and_b32_e32 v12, 31, v163
	v_lshrrev_b32_e32 v13, 5, v163
	v_xor_b32_e32 v171, 16, v163
	v_xor_b32_e32 v170, 8, v163
	v_xor_b32_e32 v169, 4, v163
	v_xor_b32_e32 v168, 2, v163
	v_xor_b32_e32 v147, 1, v163
	v_lshlrev_b32_e32 v171, 2, v171
	v_lshlrev_b32_e32 v170, 2, v170
	v_lshlrev_b32_e32 v169, 2, v169
	v_lshlrev_b32_e32 v168, 2, v168
	v_lshlrev_b32_e32 v147, 2, v147
	v_and_b32_e32 v11, 16, v163
	v_cmp_ne_u32_e64 s[0:1], 0, v11
	v_and_b32_e32 v11, 8, v163
	v_cmp_ne_u32_e64 s[4:5], 0, v11
	v_and_b32_e32 v11, 4, v163
	v_cmp_ne_u32_e64 s[98:99], 0, v11
	v_and_b32_e32 v11, 2, v163
	v_cmp_ne_u32_e64 s[100:101], 0, v11
	v_lshlrev_b32_e32 v14, 2, v12
	global_load_dword v220, v14, s[54:55] offset:0
	global_load_dword v222, v14, s[54:55] offset:128
	global_load_dword v224, v14, s[54:55] offset:256
	global_load_dword v226, v14, s[54:55] offset:384
	v_mov_b32_e32 v7, 0x358637bd
	v_mov_b32_e32 v8, 0x260
	v_pk_mul_f32 v[96:97], v[16:17], v[16:17]
	v_pk_fma_f32 v[96:97], v[32:33], v[32:33], v[96:97]
	v_pk_fma_f32 v[96:97], v[48:49], v[48:49], v[96:97]
	v_pk_fma_f32 v[96:97], v[64:65], v[64:65], v[96:97]
	v_pk_mul_f32 v[98:99], v[18:19], v[18:19]
	v_pk_fma_f32 v[98:99], v[34:35], v[34:35], v[98:99]
	v_pk_fma_f32 v[98:99], v[50:51], v[50:51], v[98:99]
	v_pk_fma_f32 v[98:99], v[66:67], v[66:67], v[98:99]
	v_pk_mul_f32 v[100:101], v[20:21], v[20:21]
	v_pk_fma_f32 v[100:101], v[36:37], v[36:37], v[100:101]
	v_pk_fma_f32 v[100:101], v[52:53], v[52:53], v[100:101]
	v_pk_fma_f32 v[100:101], v[68:69], v[68:69], v[100:101]
	v_pk_mul_f32 v[102:103], v[22:23], v[22:23]
	v_pk_fma_f32 v[102:103], v[38:39], v[38:39], v[102:103]
	v_pk_fma_f32 v[102:103], v[54:55], v[54:55], v[102:103]
	v_pk_fma_f32 v[102:103], v[70:71], v[70:71], v[102:103]
	v_pk_mul_f32 v[104:105], v[24:25], v[24:25]
	v_pk_fma_f32 v[104:105], v[40:41], v[40:41], v[104:105]
	v_pk_fma_f32 v[104:105], v[56:57], v[56:57], v[104:105]
	v_pk_fma_f32 v[104:105], v[72:73], v[72:73], v[104:105]
	v_pk_mul_f32 v[106:107], v[26:27], v[26:27]
	v_pk_fma_f32 v[106:107], v[42:43], v[42:43], v[106:107]
	v_pk_fma_f32 v[106:107], v[58:59], v[58:59], v[106:107]
	v_pk_fma_f32 v[106:107], v[74:75], v[74:75], v[106:107]
	v_pk_mul_f32 v[108:109], v[28:29], v[28:29]
	v_pk_fma_f32 v[108:109], v[44:45], v[44:45], v[108:109]
	v_pk_fma_f32 v[108:109], v[60:61], v[60:61], v[108:109]
	v_pk_fma_f32 v[108:109], v[76:77], v[76:77], v[108:109]
	v_pk_mul_f32 v[110:111], v[30:31], v[30:31]
	v_pk_fma_f32 v[110:111], v[46:47], v[46:47], v[110:111]
	v_pk_fma_f32 v[110:111], v[62:63], v[62:63], v[110:111]
	v_pk_fma_f32 v[110:111], v[78:79], v[78:79], v[110:111]
	v_cndmask_b32_e64 v112, v96, v104, s[0:1]
	v_cndmask_b32_e64 v120, v104, v96, s[0:1]
	v_cndmask_b32_e64 v113, v97, v105, s[0:1]
	v_cndmask_b32_e64 v121, v105, v97, s[0:1]
	v_cndmask_b32_e64 v114, v98, v106, s[0:1]
	v_cndmask_b32_e64 v122, v106, v98, s[0:1]
	v_cndmask_b32_e64 v115, v99, v107, s[0:1]
	v_cndmask_b32_e64 v123, v107, v99, s[0:1]
	v_cndmask_b32_e64 v116, v100, v108, s[0:1]
	v_cndmask_b32_e64 v124, v108, v100, s[0:1]
	v_cndmask_b32_e64 v117, v101, v109, s[0:1]
	v_cndmask_b32_e64 v125, v109, v101, s[0:1]
	v_cndmask_b32_e64 v118, v102, v110, s[0:1]
	v_cndmask_b32_e64 v126, v110, v102, s[0:1]
	v_cndmask_b32_e64 v119, v103, v111, s[0:1]
	v_cndmask_b32_e64 v127, v111, v103, s[0:1]
	ds_bpermute_b32 v128, v171, v120
	ds_bpermute_b32 v129, v171, v121
	ds_bpermute_b32 v130, v171, v122
	ds_bpermute_b32 v131, v171, v123
	ds_bpermute_b32 v132, v171, v124
	ds_bpermute_b32 v133, v171, v125
	ds_bpermute_b32 v134, v171, v126
	ds_bpermute_b32 v135, v171, v127
	s_waitcnt lgkmcnt(0)
	v_add_f32_e32 v112, v112, v128
	v_add_f32_e32 v113, v113, v129
	v_add_f32_e32 v114, v114, v130
	v_add_f32_e32 v115, v115, v131
	v_add_f32_e32 v116, v116, v132
	v_add_f32_e32 v117, v117, v133
	v_add_f32_e32 v118, v118, v134
	v_add_f32_e32 v119, v119, v135
	v_cndmask_b32_e64 v136, v112, v116, s[4:5]
	v_cndmask_b32_e64 v140, v116, v112, s[4:5]
	v_cndmask_b32_e64 v137, v113, v117, s[4:5]
	v_cndmask_b32_e64 v141, v117, v113, s[4:5]
	v_cndmask_b32_e64 v138, v114, v118, s[4:5]
	v_cndmask_b32_e64 v142, v118, v114, s[4:5]
	v_cndmask_b32_e64 v139, v115, v119, s[4:5]
	v_cndmask_b32_e64 v143, v119, v115, s[4:5]
	ds_bpermute_b32 v148, v170, v140
	ds_bpermute_b32 v149, v170, v141
	ds_bpermute_b32 v150, v170, v142
	ds_bpermute_b32 v151, v170, v143
	s_waitcnt lgkmcnt(0)
	v_add_f32_e32 v136, v136, v148
	v_add_f32_e32 v137, v137, v149
	v_add_f32_e32 v138, v138, v150
	v_add_f32_e32 v139, v139, v151
	v_cndmask_b32_e64 v152, v136, v138, s[98:99]
	v_cndmask_b32_e64 v154, v138, v136, s[98:99]
	v_cndmask_b32_e64 v153, v137, v139, s[98:99]
	v_cndmask_b32_e64 v155, v139, v137, s[98:99]
	ds_bpermute_b32 v156, v169, v154
	ds_bpermute_b32 v157, v169, v155
	s_waitcnt lgkmcnt(0)
; __device__ __forceinline__ unsigned cvtpk(float lo, float hi) { f32x2_t v = {lo, hi}; bf16x2_t b = __builtin_convertvector(v, bf16x2_t); return __builtin_bit_cast(unsigned, b); }
; __device__ __forceinline__ float bf_lo(unsigned u) { return __uint_as_float(u << 16); }
; __device__ __forceinline__ float bf_hi(unsigned u) { return __uint_as_float(u & 0xffff0000u); }
; __device__ __forceinline__ int crow(int r, int h) { return (r & 3) + 8 * (r >> 2) + 4 * h; }
; __device__ __forceinline__ void diff_unit(const Params& p, LAS unsigned char* lds, int b, int h, int qb, float lam) {
;     ...
;     float gn[4];
; #pragma unroll
;     for (int db = 0; db < 4; ++db) gn[db] = p.diff_gain[32 * db + c] * 0.8f;
; #pragma unroll
;     for (int r = 0; r < 16; ++r) {
;         const int qr = crow(r, hh);
;         float o[4]; float ss = 0.f;
; #pragma unroll
;         for (int db = 0; db < 4; ++db) { const unsigned w = park[(db * 8 + (r >> 1)) * 64]; o[db] = ((r & 1) ? bf_hi(w) : bf_lo(w)) - O[db][r]; ss += o[db] * o[db]; }
; #pragma unroll
;         for (int off = 1; off < 32; off <<= 1) ss += __shfl_xor(ss, off);
;         const float rs = 1.0f / sqrtf(ss * (1.0f / 128.0f) + EPS);
;         bf16_t* op = AO + (rowbase + q0 + qr) * DM + h * 128 + c;
; #pragma unroll
;         for (int db = 0; db < 4; ++db) op[32 * db] = (bf16_t)(cvtpk(o[db] * rs * gn[db], 0.f) & 0xffffu);
;     }
	v_add_f32_e32 v152, v152, v156
	v_add_f32_e32 v153, v153, v157
	v_cndmask_b32_e64 v158, v152, v153, s[100:101]
	v_cndmask_b32_e64 v159, v153, v152, s[100:101]
	ds_bpermute_b32 v166, v168, v159
	s_waitcnt lgkmcnt(0)
	v_add_f32_e32 v158, v158, v166
	ds_bpermute_b32 v166, v147, v158
	s_waitcnt lgkmcnt(0)
	v_add_f32_e32 v158, v158, v166
	v_fmamk_f32 v158, v158, 0x3c000000, v7
	v_mul_f32_e32 v2, 0x4f800000, v158
	v_cmp_gt_f32_e32 vcc, 0xf800000, v158
	s_nop 1
	v_cndmask_b32_e32 v158, v158, v2, vcc
	v_sqrt_f32_e32 v2, v158
	s_nop 0
	v_add_u32_e32 v3, -1, v2
	v_add_u32_e32 v4, 1, v2
	v_fma_f32 v5, -v3, v2, v158
	v_fma_f32 v6, -v4, v2, v158
	v_cmp_ge_f32_e64 s[0:1], 0, v5
	s_nop 1
	v_cndmask_b32_e64 v2, v2, v3, s[0:1]
	v_cmp_lt_f32_e64 s[0:1], 0, v6
	s_nop 1
	v_cndmask_b32_e64 v2, v2, v4, s[0:1]
	v_mul_f32_e32 v3, 0x37800000, v2
	v_cndmask_b32_e32 v2, v2, v3, vcc
	v_cmp_class_f32_e32 vcc, v158, v8
	s_nop 1
	v_cndmask_b32_e32 v158, v2, v158, vcc
	v_div_scale_f32 v2, s[0:1], v158, v158, 1.0
	v_rcp_f32_e32 v4, v2
	v_div_scale_f32 v3, vcc, 1.0, v158, 1.0
	v_fma_f32 v5, -v2, v4, 1.0
	v_fmac_f32_e32 v4, v5, v4
	v_mul_f32_e32 v5, v3, v4
	v_fma_f32 v6, -v2, v5, v3
	v_fmac_f32_e32 v5, v6, v4
	v_fma_f32 v2, -v2, v5, v3
	v_div_fmas_f32 v2, v2, v4, v5
	v_div_fixup_f32 v159, v2, v158, 1.0
	v_readfirstlane_b32 s1, v162
	s_nop 3
	s_lshr_b32 s1, s1, 6
	s_lshl_b32 s1, s1, 7
	s_add_u32 s1, s1, 0x10800
	v_and_b32_e32 v11, 30, v12
	v_lshlrev_b32_e32 v11, 1, v11
	v_lshl_add_u32 v11, v13, 6, v11
	v_add_u32_e32 v9, s1, v11
	v_lshlrev_b32_e32 v10, 6, v13
	v_add_u32_e32 v10, s1, v10
	ds_write_b32 v9, v159
	s_waitcnt lgkmcnt(0)
	ds_read_b128 v[176:179], v10
	ds_read_b128 v[180:183], v10 offset:16
	ds_read_b128 v[184:187], v10 offset:32
	ds_read_b128 v[216:219], v10 offset:48
	s_and_b32 s0, s72, 3
	s_lshr_b32 s1, s72, 8
	s_xor_b32 s4, s0, 7
	s_or_b32 s5, s0, 8
	s_xor_b32 s98, s0, 15
	s_cmp_eq_u32 s1, 1
	s_cselect_b32 s0, s4, s0
	s_cmp_eq_u32 s1, 2
	s_cselect_b32 s0, s5, s0
	s_cmp_eq_u32 s1, 3
	s_cselect_b32 s0, s98, s0
	v_readfirstlane_b32 s1, v162
	s_nop 3
	s_lshr_b32 s1, s1, 6
	s_lshl_b32 s0, s0, 8
	s_lshl_b32 s1, s1, 5
	s_add_u32 s0, s0, s1
	s_bfe_u32 s1, s72, 0x30005
	s_lshl_b32 s1, s1, 12
	s_add_u32 s0, s0, s1
	s_lshl_b32 s4, s0, 12
	s_bfe_u32 s1, s72, 0x30002
	s_lshl_b32 s1, s1, 8
	s_add_u32 s4, s4, s1
	s_add_u32 s0, s28, 0x2e000000
	s_addc_u32 s1, s29, 0
	s_add_u32 s0, s0, s4
	s_addc_u32 s1, s1, 0
	s_add_u32 s4, s0, 0x10000
	s_addc_u32 s5, s1, 0
	v_lshlrev_b32_e32 v11, 14, v13
	v_lshl_add_u32 v11, v12, 1, v11
	v_mov_b32_e32 v228, v11
	v_add_u32_e32 v229, 0x1000, v11
	v_add_u32_e32 v230, 0x2000, v11
	v_add_u32_e32 v231, 0x3000, v11
	v_add_u32_e32 v232, 0x8000, v11
	v_add_u32_e32 v233, 0x9000, v11
	v_add_u32_e32 v234, 0xa000, v11
	v_add_u32_e32 v235, 0xb000, v11
	s_waitcnt vmcnt(0) lgkmcnt(0)
	v_mul_f32_e32 v220, 0x3f4ccccd, v220
	v_mul_f32_e32 v222, 0x3f4ccccd, v222
	v_mul_f32_e32 v224, 0x3f4ccccd, v224
	v_mul_f32_e32 v226, 0x3f4ccccd, v226
	v_pk_mul_f32 v[236:237], v[16:17], v[176:177]
	v_pk_mul_f32 v[236:237], v[236:237], v[220:221] op_sel_hi:[1,0]
	v_cvt_pk_bf16_f32 v240, v236, v237
	global_store_short v228, v240, s[0:1]
	global_store_short_d16_hi v229, v240, s[0:1]
	v_pk_mul_f32 v[238:239], v[18:19], v[178:179]
	v_pk_mul_f32 v[238:239], v[238:239], v[220:221] op_sel_hi:[1,0]
	v_cvt_pk_bf16_f32 v241, v238, v239
	global_store_short v230, v241, s[0:1]
	global_store_short_d16_hi v231, v241, s[0:1]
	v_pk_mul_f32 v[236:237], v[20:21], v[180:181]
	v_pk_mul_f32 v[236:237], v[236:237], v[220:221] op_sel_hi:[1,0]
	v_cvt_pk_bf16_f32 v242, v236, v237
	global_store_short v232, v242, s[0:1]
	global_store_short_d16_hi v233, v242, s[0:1]
	v_pk_mul_f32 v[238:239], v[22:23], v[182:183]
	v_pk_mul_f32 v[238:239], v[238:239], v[220:221] op_sel_hi:[1,0]
	v_cvt_pk_bf16_f32 v243, v238, v239
	global_store_short v234, v243, s[0:1]
	global_store_short_d16_hi v235, v243, s[0:1]
	v_pk_mul_f32 v[236:237], v[24:25], v[184:185]
	v_pk_mul_f32 v[236:237], v[236:237], v[220:221] op_sel_hi:[1,0]
	v_cvt_pk_bf16_f32 v244, v236, v237
	global_store_short v228, v244, s[4:5]
	global_store_short_d16_hi v229, v244, s[4:5]
	v_pk_mul_f32 v[238:239], v[26:27], v[186:187]
	v_pk_mul_f32 v[238:239], v[238:239], v[220:221] op_sel_hi:[1,0]
	v_cvt_pk_bf16_f32 v213, v238, v239
	global_store_short v230, v213, s[4:5]
	global_store_short_d16_hi v231, v213, s[4:5]
	v_pk_mul_f32 v[236:237], v[28:29], v[216:217]
	v_pk_mul_f32 v[236:237], v[236:237], v[220:221] op_sel_hi:[1,0]
	v_cvt_pk_bf16_f32 v214, v236, v237
	global_store_short v232, v214, s[4:5]
	global_store_short_d16_hi v233, v214, s[4:5]
	v_pk_mul_f32 v[238:239], v[30:31], v[218:219]
	v_pk_mul_f32 v[238:239], v[238:239], v[220:221] op_sel_hi:[1,0]
	v_cvt_pk_bf16_f32 v215, v238, v239
	global_store_short v234, v215, s[4:5]
	global_store_short_d16_hi v235, v215, s[4:5]
	v_pk_mul_f32 v[236:237], v[32:33], v[176:177]
	v_pk_mul_f32 v[236:237], v[236:237], v[222:223] op_sel_hi:[1,0]
	v_cvt_pk_bf16_f32 v240, v236, v237
	global_store_short v228, v240, s[0:1] offset:64
	global_store_short_d16_hi v229, v240, s[0:1] offset:64
	v_pk_mul_f32 v[238:239], v[34:35], v[178:179]
	v_pk_mul_f32 v[238:239], v[238:239], v[222:223] op_sel_hi:[1,0]
	v_cvt_pk_bf16_f32 v241, v238, v239
	global_store_short v230, v241, s[0:1] offset:64
	global_store_short_d16_hi v231, v241, s[0:1] offset:64
	v_pk_mul_f32 v[236:237], v[36:37], v[180:181]
	v_pk_mul_f32 v[236:237], v[236:237], v[222:223] op_sel_hi:[1,0]
	v_cvt_pk_bf16_f32 v242, v236, v237
	global_store_short v232, v242, s[0:1] offset:64
; __device__ __forceinline__ unsigned cvtpk(float lo, float hi) { f32x2_t v = {lo, hi}; bf16x2_t b = __builtin_convertvector(v, bf16x2_t); return __builtin_bit_cast(unsigned, b); }
; __device__ __forceinline__ void diff_unit(const Params& p, LAS unsigned char* lds, int b, int h, int qb, float lam) {
;     ...
;         bf16_t* op = AO + (rowbase + q0 + qr) * DM + h * 128 + c;
; #pragma unroll
;         for (int db = 0; db < 4; ++db) op[32 * db] = (bf16_t)(cvtpk(o[db] * rs * gn[db], 0.f) & 0xffffu);
	global_store_short_d16_hi v233, v242, s[0:1] offset:64
	v_pk_mul_f32 v[238:239], v[38:39], v[182:183]
	v_pk_mul_f32 v[238:239], v[238:239], v[222:223] op_sel_hi:[1,0]
	v_cvt_pk_bf16_f32 v243, v238, v239
	global_store_short v234, v243, s[0:1] offset:64
	global_store_short_d16_hi v235, v243, s[0:1] offset:64
	v_pk_mul_f32 v[236:237], v[40:41], v[184:185]
	v_pk_mul_f32 v[236:237], v[236:237], v[222:223] op_sel_hi:[1,0]
	v_cvt_pk_bf16_f32 v244, v236, v237
	global_store_short v228, v244, s[4:5] offset:64
	global_store_short_d16_hi v229, v244, s[4:5] offset:64
	v_pk_mul_f32 v[238:239], v[42:43], v[186:187]
	v_pk_mul_f32 v[238:239], v[238:239], v[222:223] op_sel_hi:[1,0]
	v_cvt_pk_bf16_f32 v213, v238, v239
	global_store_short v230, v213, s[4:5] offset:64
	global_store_short_d16_hi v231, v213, s[4:5] offset:64
	v_pk_mul_f32 v[236:237], v[44:45], v[216:217]
	v_pk_mul_f32 v[236:237], v[236:237], v[222:223] op_sel_hi:[1,0]
	v_cvt_pk_bf16_f32 v214, v236, v237
	global_store_short v232, v214, s[4:5] offset:64
	global_store_short_d16_hi v233, v214, s[4:5] offset:64
	v_pk_mul_f32 v[238:239], v[46:47], v[218:219]
	v_pk_mul_f32 v[238:239], v[238:239], v[222:223] op_sel_hi:[1,0]
	v_cvt_pk_bf16_f32 v215, v238, v239
	global_store_short v234, v215, s[4:5] offset:64
	global_store_short_d16_hi v235, v215, s[4:5] offset:64
	v_pk_mul_f32 v[236:237], v[48:49], v[176:177]
	v_pk_mul_f32 v[236:237], v[236:237], v[224:225] op_sel_hi:[1,0]
	v_cvt_pk_bf16_f32 v240, v236, v237
	global_store_short v228, v240, s[0:1] offset:128
	global_store_short_d16_hi v229, v240, s[0:1] offset:128
	v_pk_mul_f32 v[238:239], v[50:51], v[178:179]
	v_pk_mul_f32 v[238:239], v[238:239], v[224:225] op_sel_hi:[1,0]
	v_cvt_pk_bf16_f32 v241, v238, v239
	global_store_short v230, v241, s[0:1] offset:128
	global_store_short_d16_hi v231, v241, s[0:1] offset:128
	v_pk_mul_f32 v[236:237], v[52:53], v[180:181]
	v_pk_mul_f32 v[236:237], v[236:237], v[224:225] op_sel_hi:[1,0]
	v_cvt_pk_bf16_f32 v242, v236, v237
	global_store_short v232, v242, s[0:1] offset:128
	global_store_short_d16_hi v233, v242, s[0:1] offset:128
	v_pk_mul_f32 v[238:239], v[54:55], v[182:183]
	v_pk_mul_f32 v[238:239], v[238:239], v[224:225] op_sel_hi:[1,0]
	v_cvt_pk_bf16_f32 v243, v238, v239
	global_store_short v234, v243, s[0:1] offset:128
	global_store_short_d16_hi v235, v243, s[0:1] offset:128
	v_pk_mul_f32 v[236:237], v[56:57], v[184:185]
	v_pk_mul_f32 v[236:237], v[236:237], v[224:225] op_sel_hi:[1,0]
	v_cvt_pk_bf16_f32 v244, v236, v237
	global_store_short v228, v244, s[4:5] offset:128
	global_store_short_d16_hi v229, v244, s[4:5] offset:128
	v_pk_mul_f32 v[238:239], v[58:59], v[186:187]
	v_pk_mul_f32 v[238:239], v[238:239], v[224:225] op_sel_hi:[1,0]
	v_cvt_pk_bf16_f32 v213, v238, v239
	global_store_short v230, v213, s[4:5] offset:128
	global_store_short_d16_hi v231, v213, s[4:5] offset:128
	v_pk_mul_f32 v[236:237], v[60:61], v[216:217]
	v_pk_mul_f32 v[236:237], v[236:237], v[224:225] op_sel_hi:[1,0]
	v_cvt_pk_bf16_f32 v214, v236, v237
	global_store_short v232, v214, s[4:5] offset:128
	global_store_short_d16_hi v233, v214, s[4:5] offset:128
	v_pk_mul_f32 v[238:239], v[62:63], v[218:219]
	v_pk_mul_f32 v[238:239], v[238:239], v[224:225] op_sel_hi:[1,0]
	v_cvt_pk_bf16_f32 v215, v238, v239
	global_store_short v234, v215, s[4:5] offset:128
	global_store_short_d16_hi v235, v215, s[4:5] offset:128
	v_pk_mul_f32 v[236:237], v[64:65], v[176:177]
	v_pk_mul_f32 v[236:237], v[236:237], v[226:227] op_sel_hi:[1,0]
	v_cvt_pk_bf16_f32 v240, v236, v237
	global_store_short v228, v240, s[0:1] offset:192
	global_store_short_d16_hi v229, v240, s[0:1] offset:192
	v_pk_mul_f32 v[238:239], v[66:67], v[178:179]
	v_pk_mul_f32 v[238:239], v[238:239], v[226:227] op_sel_hi:[1,0]
	v_cvt_pk_bf16_f32 v241, v238, v239
	global_store_short v230, v241, s[0:1] offset:192
	global_store_short_d16_hi v231, v241, s[0:1] offset:192
	v_pk_mul_f32 v[236:237], v[68:69], v[180:181]
	v_pk_mul_f32 v[236:237], v[236:237], v[226:227] op_sel_hi:[1,0]
	v_cvt_pk_bf16_f32 v242, v236, v237
	global_store_short v232, v242, s[0:1] offset:192
	global_store_short_d16_hi v233, v242, s[0:1] offset:192
	v_pk_mul_f32 v[238:239], v[70:71], v[182:183]
	v_pk_mul_f32 v[238:239], v[238:239], v[226:227] op_sel_hi:[1,0]
	v_cvt_pk_bf16_f32 v243, v238, v239
	global_store_short v234, v243, s[0:1] offset:192
	global_store_short_d16_hi v235, v243, s[0:1] offset:192
	v_pk_mul_f32 v[236:237], v[72:73], v[184:185]
	v_pk_mul_f32 v[236:237], v[236:237], v[226:227] op_sel_hi:[1,0]
	v_cvt_pk_bf16_f32 v244, v236, v237
	global_store_short v228, v244, s[4:5] offset:192
	global_store_short_d16_hi v229, v244, s[4:5] offset:192
	v_pk_mul_f32 v[238:239], v[74:75], v[186:187]
	v_pk_mul_f32 v[238:239], v[238:239], v[226:227] op_sel_hi:[1,0]
	v_cvt_pk_bf16_f32 v213, v238, v239
	global_store_short v230, v213, s[4:5] offset:192
	global_store_short_d16_hi v231, v213, s[4:5] offset:192
	v_pk_mul_f32 v[236:237], v[76:77], v[216:217]
	v_pk_mul_f32 v[236:237], v[236:237], v[226:227] op_sel_hi:[1,0]
	v_cvt_pk_bf16_f32 v214, v236, v237
	global_store_short v232, v214, s[4:5] offset:192
	global_store_short_d16_hi v233, v214, s[4:5] offset:192
	v_pk_mul_f32 v[238:239], v[78:79], v[218:219]
	v_pk_mul_f32 v[238:239], v[238:239], v[226:227] op_sel_hi:[1,0]
	v_cvt_pk_bf16_f32 v215, v238, v239
	global_store_short v234, v215, s[4:5] offset:192
	global_store_short_d16_hi v235, v215, s[4:5] offset:192
	v_add_u32_e32 v80, 64, v194
	s_add_i32 s72, s72, s30
	s_cmpk_lt_i32 s72, 0x400
	s_cbranch_scc0 .LBB0_315

; #define LAS __attribute__((address_space(3)))
; __device__ __forceinline__ unsigned cvtpk(float lo, float hi) { f32x2_t v = {lo, hi}; bf16x2_t b = __builtin_convertvector(v, bf16x2_t); return __builtin_bit_cast(unsigned, b); }
; __device__ __forceinline__ int crow(int r, int h) { return (r & 3) + 8 * (r >> 2) + 4 * h; }
; __device__ __forceinline__ void sb_unit(const Params& p, LAS unsigned char* lds, int b, int h, int qb) {
;     ...
;         if (lane == 0) flag[cur * 8 + wid] = done ? 1u : 0u;
;         asm volatile("s_waitcnt vmcnt(0)" ::: "memory");
;         __syncthreads();
;         const u32x4 f0 = *(const LAS u32x4*)(flag + cur * 8), f1 = *(const LAS u32x4*)(flag + cur * 8 + 4);
;         if ((f0.x & f0.y & f0.z & f0.w & f1.x & f1.y & f1.z & f1.w) != 0u) break;
;     }
;     float gn[4];
; #pragma unroll
;     for (int db = 0; db < 4; ++db) gn[db] = p.sb_gain[32 * db + c];
; #pragma unroll
;     for (int r = 0; r < 16; ++r) {
;         const int qr = crow(r, hh);
;         float ss = 0.f;
; #pragma unroll
;         for (int db = 0; db < 4; ++db) ss += O[db][r] * O[db][r];
; #pragma unroll
;         for (int off = 1; off < 32; off <<= 1) ss += __shfl_xor(ss, off);
;         const float rs = 1.0f / sqrtf(ss * (1.0f / 128.0f) + EPS);
;         bf16_t* op = AO + (rowbase + q0 + qr) * DM + 1024 + h * 128 + c;
; #pragma unroll
;         for (int db = 0; db < 4; ++db) op[32 * db] = (bf16_t)(cvtpk(O[db][r] * rs * gn[db], 0.f) & 0xffffu);
;     }
.LBB0_327:
	s_lshl_b32 s10, s10, 5
	s_and_saveexec_b64 s[14:15], s[4:5]
	s_add_i32 s34, s48, s10
	v_cndmask_b32_e64 v64, 0, 1, s[8:9]
	v_mov_b32_e32 v65, s34
	ds_write_b32 v65, v64
	s_or_b64 exec, exec, s[14:15]
	s_add_i32 s10, s10, 0
	s_add_i32 s10, s10, 0x10400
	v_mov_b32_e32 v68, s10
	s_waitcnt vmcnt(0)
	s_waitcnt vmcnt(0) lgkmcnt(0)
	s_barrier
	ds_read_b128 v[64:67], v68
	ds_read_b128 v[68:71], v68 offset:16
	s_add_i32 s10, s23, -1
	s_cmp_lg_u32 s23, 0
	s_cselect_b64 s[14:15], -1, 0
	s_waitcnt lgkmcnt(1)
	v_and_b32_e32 v64, v64, v65
	v_and_b32_e32 v64, v64, v66
	v_and_b32_e32 v64, v64, v67
	s_waitcnt lgkmcnt(0)
	v_and_b32_e32 v64, v64, v68
	v_and_b32_e32 v64, v64, v69
	v_and_b32_e32 v64, v64, v70
	v_and_b32_e32 v64, v64, v71
	v_cmp_eq_u32_e32 vcc, 0, v64
	s_and_b64 s[14:15], s[14:15], vcc
	v_add_u32_e32 v191, 64, v191
	s_and_b64 vcc, exec, s[14:15]
	s_cbranch_vccnz .LBB0_323
	v_and_b32_e32 v224, 31, v163
	v_lshrrev_b32_e32 v225, 5, v163
	v_xor_b32_e32 v226, 16, v163
	v_xor_b32_e32 v227, 8, v163
	v_xor_b32_e32 v228, 4, v163
	v_xor_b32_e32 v229, 2, v163
	v_xor_b32_e32 v230, 1, v163
	v_lshlrev_b32_e32 v226, 2, v226
	v_lshlrev_b32_e32 v227, 2, v227
	v_lshlrev_b32_e32 v228, 2, v228
	v_lshlrev_b32_e32 v229, 2, v229
	v_lshlrev_b32_e32 v230, 2, v230
	v_and_b32_e32 v135, 16, v163
	v_cmp_ne_u32_e64 s[0:1], 0, v135
	v_and_b32_e32 v135, 8, v163
	v_cmp_ne_u32_e64 s[4:5], 0, v135
	v_and_b32_e32 v135, 4, v163
	v_cmp_ne_u32_e64 s[98:99], 0, v135
	v_and_b32_e32 v135, 2, v163
	v_cmp_ne_u32_e64 s[100:101], 0, v135
	v_lshlrev_b32_e32 v231, 2, v224
	global_load_dword v196, v231, s[56:57] offset:0
	global_load_dword v198, v231, s[56:57] offset:128
	global_load_dword v200, v231, s[56:57] offset:256
	global_load_dword v202, v231, s[56:57] offset:384
	v_mov_b32_e32 v131, 0x358637bd
	v_mov_b32_e32 v132, 0x260
	v_pk_mul_f32 v[64:65], v[0:1], v[0:1]
	v_pk_fma_f32 v[64:65], v[48:49], v[48:49], v[64:65]
	v_pk_fma_f32 v[64:65], v[32:33], v[32:33], v[64:65]
	v_pk_fma_f32 v[64:65], v[16:17], v[16:17], v[64:65]
	v_pk_mul_f32 v[66:67], v[2:3], v[2:3]
	v_pk_fma_f32 v[66:67], v[50:51], v[50:51], v[66:67]
	v_pk_fma_f32 v[66:67], v[34:35], v[34:35], v[66:67]
	v_pk_fma_f32 v[66:67], v[18:19], v[18:19], v[66:67]
	v_pk_mul_f32 v[68:69], v[4:5], v[4:5]
	v_pk_fma_f32 v[68:69], v[52:53], v[52:53], v[68:69]
	v_pk_fma_f32 v[68:69], v[36:37], v[36:37], v[68:69]
	v_pk_fma_f32 v[68:69], v[20:21], v[20:21], v[68:69]
	v_pk_mul_f32 v[70:71], v[6:7], v[6:7]
	v_pk_fma_f32 v[70:71], v[54:55], v[54:55], v[70:71]
	v_pk_fma_f32 v[70:71], v[38:39], v[38:39], v[70:71]
	v_pk_fma_f32 v[70:71], v[22:23], v[22:23], v[70:71]
	v_pk_mul_f32 v[72:73], v[8:9], v[8:9]
	v_pk_fma_f32 v[72:73], v[56:57], v[56:57], v[72:73]
	v_pk_fma_f32 v[72:73], v[40:41], v[40:41], v[72:73]
	v_pk_fma_f32 v[72:73], v[24:25], v[24:25], v[72:73]
	v_pk_mul_f32 v[74:75], v[10:11], v[10:11]
	v_pk_fma_f32 v[74:75], v[58:59], v[58:59], v[74:75]
	v_pk_fma_f32 v[74:75], v[42:43], v[42:43], v[74:75]
	v_pk_fma_f32 v[74:75], v[26:27], v[26:27], v[74:75]
	v_pk_mul_f32 v[76:77], v[12:13], v[12:13]
	v_pk_fma_f32 v[76:77], v[60:61], v[60:61], v[76:77]
	v_pk_fma_f32 v[76:77], v[44:45], v[44:45], v[76:77]
	v_pk_fma_f32 v[76:77], v[28:29], v[28:29], v[76:77]
	v_pk_mul_f32 v[78:79], v[14:15], v[14:15]
	v_pk_fma_f32 v[78:79], v[62:63], v[62:63], v[78:79]
	v_pk_fma_f32 v[78:79], v[46:47], v[46:47], v[78:79]
	v_pk_fma_f32 v[78:79], v[30:31], v[30:31], v[78:79]
	v_cndmask_b32_e64 v80, v64, v72, s[0:1]
	v_cndmask_b32_e64 v88, v72, v64, s[0:1]
	v_cndmask_b32_e64 v81, v65, v73, s[0:1]
	v_cndmask_b32_e64 v89, v73, v65, s[0:1]
	v_cndmask_b32_e64 v82, v66, v74, s[0:1]
	v_cndmask_b32_e64 v90, v74, v66, s[0:1]
	v_cndmask_b32_e64 v83, v67, v75, s[0:1]
	v_cndmask_b32_e64 v91, v75, v67, s[0:1]
	v_cndmask_b32_e64 v84, v68, v76, s[0:1]
	v_cndmask_b32_e64 v92, v76, v68, s[0:1]
	v_cndmask_b32_e64 v85, v69, v77, s[0:1]
	v_cndmask_b32_e64 v93, v77, v69, s[0:1]
	v_cndmask_b32_e64 v86, v70, v78, s[0:1]
	v_cndmask_b32_e64 v94, v78, v70, s[0:1]
	v_cndmask_b32_e64 v87, v71, v79, s[0:1]
	v_cndmask_b32_e64 v95, v79, v71, s[0:1]
	ds_bpermute_b32 v96, v226, v88
	ds_bpermute_b32 v97, v226, v89
	ds_bpermute_b32 v98, v226, v90
	ds_bpermute_b32 v99, v226, v91
	ds_bpermute_b32 v100, v226, v92
	ds_bpermute_b32 v101, v226, v93
	ds_bpermute_b32 v102, v226, v94
	ds_bpermute_b32 v103, v226, v95
	s_waitcnt lgkmcnt(0)
	v_add_f32_e32 v80, v80, v96
	v_add_f32_e32 v81, v81, v97
	v_add_f32_e32 v82, v82, v98
	v_add_f32_e32 v83, v83, v99
	v_add_f32_e32 v84, v84, v100
	v_add_f32_e32 v85, v85, v101
	v_add_f32_e32 v86, v86, v102
	v_add_f32_e32 v87, v87, v103
	v_cndmask_b32_e64 v104, v80, v84, s[4:5]
	v_cndmask_b32_e64 v108, v84, v80, s[4:5]
	v_cndmask_b32_e64 v105, v81, v85, s[4:5]
	v_cndmask_b32_e64 v109, v85, v81, s[4:5]
	v_cndmask_b32_e64 v106, v82, v86, s[4:5]
	v_cndmask_b32_e64 v110, v86, v82, s[4:5]
	v_cndmask_b32_e64 v107, v83, v87, s[4:5]
	v_cndmask_b32_e64 v111, v87, v83, s[4:5]
	ds_bpermute_b32 v112, v227, v108
	ds_bpermute_b32 v113, v227, v109
	ds_bpermute_b32 v114, v227, v110
	ds_bpermute_b32 v115, v227, v111
	s_waitcnt lgkmcnt(0)
	v_add_f32_e32 v104, v104, v112
	v_add_f32_e32 v105, v105, v113
	v_add_f32_e32 v106, v106, v114
	v_add_f32_e32 v107, v107, v115
	v_cndmask_b32_e64 v116, v104, v106, s[98:99]
	v_cndmask_b32_e64 v118, v106, v104, s[98:99]
	v_cndmask_b32_e64 v117, v105, v107, s[98:99]
	v_cndmask_b32_e64 v119, v107, v105, s[98:99]
	ds_bpermute_b32 v120, v228, v118
	ds_bpermute_b32 v121, v228, v119
	s_waitcnt lgkmcnt(0)
	v_add_f32_e32 v116, v116, v120
	v_add_f32_e32 v117, v117, v121
	v_cndmask_b32_e64 v122, v116, v117, s[100:101]
	v_cndmask_b32_e64 v123, v117, v116, s[100:101]
	ds_bpermute_b32 v124, v229, v123
	s_waitcnt lgkmcnt(0)
; __device__ __forceinline__ unsigned cvtpk(float lo, float hi) { f32x2_t v = {lo, hi}; bf16x2_t b = __builtin_convertvector(v, bf16x2_t); return __builtin_bit_cast(unsigned, b); }
; __device__ __forceinline__ int crow(int r, int h) { return (r & 3) + 8 * (r >> 2) + 4 * h; }
; __device__ __forceinline__ void sb_unit(const Params& p, LAS unsigned char* lds, int b, int h, int qb) {
;     ...
; #pragma unroll
;     for (int r = 0; r < 16; ++r) {
;         const int qr = crow(r, hh);
;         float ss = 0.f;
; #pragma unroll
;         for (int db = 0; db < 4; ++db) ss += O[db][r] * O[db][r];
; #pragma unroll
;         for (int off = 1; off < 32; off <<= 1) ss += __shfl_xor(ss, off);
;         const float rs = 1.0f / sqrtf(ss * (1.0f / 128.0f) + EPS);
;         bf16_t* op = AO + (rowbase + q0 + qr) * DM + 1024 + h * 128 + c;
; #pragma unroll
;         for (int db = 0; db < 4; ++db) op[32 * db] = (bf16_t)(cvtpk(O[db][r] * rs * gn[db], 0.f) & 0xffffu);
	v_add_f32_e32 v122, v122, v124
	ds_bpermute_b32 v124, v230, v122
	s_waitcnt lgkmcnt(0)
	v_add_f32_e32 v122, v122, v124
	v_fmamk_f32 v122, v122, 0x3c000000, v131
	v_mul_f32_e32 v126, 0x4f800000, v122
	v_cmp_gt_f32_e32 vcc, 0xf800000, v122
	s_nop 1
	v_cndmask_b32_e32 v122, v122, v126, vcc
	v_sqrt_f32_e32 v126, v122
	s_nop 0
	v_add_u32_e32 v127, -1, v126
	v_add_u32_e32 v128, 1, v126
	v_fma_f32 v129, -v127, v126, v122
	v_fma_f32 v130, -v128, v126, v122
	v_cmp_ge_f32_e64 s[0:1], 0, v129
	s_nop 1
	v_cndmask_b32_e64 v126, v126, v127, s[0:1]
	v_cmp_lt_f32_e64 s[0:1], 0, v130
	s_nop 1
	v_cndmask_b32_e64 v126, v126, v128, s[0:1]
	v_mul_f32_e32 v127, 0x37800000, v126
	v_cndmask_b32_e32 v126, v126, v127, vcc
	v_cmp_class_f32_e32 vcc, v122, v132
	s_nop 1
	v_cndmask_b32_e32 v122, v126, v122, vcc
	v_div_scale_f32 v126, s[0:1], v122, v122, 1.0
	v_rcp_f32_e32 v128, v126
	v_div_scale_f32 v127, vcc, 1.0, v122, 1.0
	v_fma_f32 v129, -v126, v128, 1.0
	v_fmac_f32_e32 v128, v129, v128
	v_mul_f32_e32 v129, v127, v128
	v_fma_f32 v130, -v126, v129, v127
	v_fmac_f32_e32 v129, v130, v128
	v_fma_f32 v126, -v126, v129, v127
	v_div_fmas_f32 v126, v126, v128, v129
	v_div_fixup_f32 v123, v126, v122, 1.0
	v_readfirstlane_b32 s1, v162
	s_nop 3
	s_lshr_b32 s1, s1, 6
	s_lshl_b32 s1, s1, 7
	s_add_u32 s1, s1, 0x10800
	v_and_b32_e32 v135, 30, v224
	v_lshlrev_b32_e32 v135, 1, v135
	v_lshl_add_u32 v135, v225, 6, v135
	v_add_u32_e32 v133, s1, v135
	v_lshlrev_b32_e32 v134, 6, v225
	v_add_u32_e32 v134, s1, v134
	ds_write_b32 v133, v123
	s_waitcnt lgkmcnt(0)
	ds_read_b128 v[176:179], v134
	ds_read_b128 v[180:183], v134 offset:16
	ds_read_b128 v[184:187], v134 offset:32
	ds_read_b128 v[192:195], v134 offset:48
	s_and_b32 s0, s16, 3
	s_lshr_b32 s1, s16, 8
	s_xor_b32 s4, s0, 7
	s_or_b32 s5, s0, 8
	s_xor_b32 s10, s0, 15
	s_cmp_eq_u32 s1, 1
	s_cselect_b32 s0, s4, s0
	s_cmp_eq_u32 s1, 2
	s_cselect_b32 s0, s5, s0
	s_cmp_eq_u32 s1, 3
	s_cselect_b32 s0, s10, s0
	v_readfirstlane_b32 s1, v162
	s_nop 3
	s_lshr_b32 s1, s1, 6
	s_lshl_b32 s0, s0, 8
	s_lshl_b32 s1, s1, 5
	s_add_u32 s0, s0, s1
	s_bfe_u32 s1, s16, 0x30005
	s_lshl_b32 s1, s1, 12
	s_add_u32 s0, s0, s1
	s_lshl_b32 s4, s0, 12
	s_bfe_u32 s1, s16, 0x30002
	s_lshl_b32 s1, s1, 8
	s_add_u32 s4, s4, s1
	s_add_u32 s4, s4, 0x800
	s_add_u32 s0, s28, 0x2e000000
	s_addc_u32 s1, s29, 0
	s_add_u32 s0, s0, s4
	s_addc_u32 s1, s1, 0
	s_add_u32 s4, s0, 0x10000
	s_addc_u32 s5, s1, 0
	v_lshlrev_b32_e32 v135, 14, v225
	v_lshl_add_u32 v135, v224, 1, v135
	v_mov_b32_e32 v204, v135
	v_add_u32_e32 v205, 0x1000, v135
	v_add_u32_e32 v206, 0x2000, v135
	v_add_u32_e32 v207, 0x3000, v135
	v_add_u32_e32 v208, 0x8000, v135
	v_add_u32_e32 v209, 0x9000, v135
	v_add_u32_e32 v210, 0xa000, v135
	v_add_u32_e32 v211, 0xb000, v135
	s_waitcnt vmcnt(0) lgkmcnt(0)
	v_pk_mul_f32 v[212:213], v[0:1], v[176:177]
	v_pk_mul_f32 v[212:213], v[212:213], v[196:197] op_sel_hi:[1,0]
	v_cvt_pk_bf16_f32 v216, v212, v213
	global_store_short v204, v216, s[0:1]
	global_store_short_d16_hi v205, v216, s[0:1]
	v_pk_mul_f32 v[214:215], v[2:3], v[178:179]
	v_pk_mul_f32 v[214:215], v[214:215], v[196:197] op_sel_hi:[1,0]
	v_cvt_pk_bf16_f32 v217, v214, v215
	global_store_short v206, v217, s[0:1]
	global_store_short_d16_hi v207, v217, s[0:1]
	v_pk_mul_f32 v[212:213], v[4:5], v[180:181]
	v_pk_mul_f32 v[212:213], v[212:213], v[196:197] op_sel_hi:[1,0]
	v_cvt_pk_bf16_f32 v218, v212, v213
	global_store_short v208, v218, s[0:1]
	global_store_short_d16_hi v209, v218, s[0:1]
	v_pk_mul_f32 v[214:215], v[6:7], v[182:183]
	v_pk_mul_f32 v[214:215], v[214:215], v[196:197] op_sel_hi:[1,0]
	v_cvt_pk_bf16_f32 v219, v214, v215
	global_store_short v210, v219, s[0:1]
	global_store_short_d16_hi v211, v219, s[0:1]
	v_pk_mul_f32 v[212:213], v[8:9], v[184:185]
	v_pk_mul_f32 v[212:213], v[212:213], v[196:197] op_sel_hi:[1,0]
	v_cvt_pk_bf16_f32 v220, v212, v213
	global_store_short v204, v220, s[4:5]
	global_store_short_d16_hi v205, v220, s[4:5]
	v_pk_mul_f32 v[214:215], v[10:11], v[186:187]
	v_pk_mul_f32 v[214:215], v[214:215], v[196:197] op_sel_hi:[1,0]
	v_cvt_pk_bf16_f32 v221, v214, v215
	global_store_short v206, v221, s[4:5]
	global_store_short_d16_hi v207, v221, s[4:5]
	v_pk_mul_f32 v[212:213], v[12:13], v[192:193]
	v_pk_mul_f32 v[212:213], v[212:213], v[196:197] op_sel_hi:[1,0]
	v_cvt_pk_bf16_f32 v222, v212, v213
	global_store_short v208, v222, s[4:5]
	global_store_short_d16_hi v209, v222, s[4:5]
	v_pk_mul_f32 v[214:215], v[14:15], v[194:195]
	v_pk_mul_f32 v[214:215], v[214:215], v[196:197] op_sel_hi:[1,0]
	v_cvt_pk_bf16_f32 v223, v214, v215
	global_store_short v210, v223, s[4:5]
	global_store_short_d16_hi v211, v223, s[4:5]
	v_pk_mul_f32 v[212:213], v[48:49], v[176:177]
	v_pk_mul_f32 v[212:213], v[212:213], v[198:199] op_sel_hi:[1,0]
	v_cvt_pk_bf16_f32 v216, v212, v213
	global_store_short v204, v216, s[0:1] offset:64
	global_store_short_d16_hi v205, v216, s[0:1] offset:64
	v_pk_mul_f32 v[214:215], v[50:51], v[178:179]
	v_pk_mul_f32 v[214:215], v[214:215], v[198:199] op_sel_hi:[1,0]
	v_cvt_pk_bf16_f32 v217, v214, v215
	global_store_short v206, v217, s[0:1] offset:64
	global_store_short_d16_hi v207, v217, s[0:1] offset:64
	v_pk_mul_f32 v[212:213], v[52:53], v[180:181]
	v_pk_mul_f32 v[212:213], v[212:213], v[198:199] op_sel_hi:[1,0]
	v_cvt_pk_bf16_f32 v218, v212, v213
	global_store_short v208, v218, s[0:1] offset:64
	global_store_short_d16_hi v209, v218, s[0:1] offset:64
	v_pk_mul_f32 v[214:215], v[54:55], v[182:183]
; __device__ __forceinline__ unsigned cvtpk(float lo, float hi) { f32x2_t v = {lo, hi}; bf16x2_t b = __builtin_convertvector(v, bf16x2_t); return __builtin_bit_cast(unsigned, b); }
; __device__ __forceinline__ int crow(int r, int h) { return (r & 3) + 8 * (r >> 2) + 4 * h; }
; __device__ __forceinline__ void sb_unit(const Params& p, LAS unsigned char* lds, int b, int h, int qb) {
;     ...
; #pragma unroll
;     for (int r = 0; r < 16; ++r) {
;         const int qr = crow(r, hh);
;         float ss = 0.f;
; #pragma unroll
;         for (int db = 0; db < 4; ++db) ss += O[db][r] * O[db][r];
; #pragma unroll
;         for (int off = 1; off < 32; off <<= 1) ss += __shfl_xor(ss, off);
;         const float rs = 1.0f / sqrtf(ss * (1.0f / 128.0f) + EPS);
;         bf16_t* op = AO + (rowbase + q0 + qr) * DM + 1024 + h * 128 + c;
; #pragma unroll
;         for (int db = 0; db < 4; ++db) op[32 * db] = (bf16_t)(cvtpk(O[db][r] * rs * gn[db], 0.f) & 0xffffu);
;     }
;     asm volatile("s_waitcnt vmcnt(0)" ::: "memory");
;     __syncthreads();
	v_pk_mul_f32 v[214:215], v[214:215], v[198:199] op_sel_hi:[1,0]
	v_cvt_pk_bf16_f32 v219, v214, v215
	global_store_short v210, v219, s[0:1] offset:64
	global_store_short_d16_hi v211, v219, s[0:1] offset:64
	v_pk_mul_f32 v[212:213], v[56:57], v[184:185]
	v_pk_mul_f32 v[212:213], v[212:213], v[198:199] op_sel_hi:[1,0]
	v_cvt_pk_bf16_f32 v220, v212, v213
	global_store_short v204, v220, s[4:5] offset:64
	global_store_short_d16_hi v205, v220, s[4:5] offset:64
	v_pk_mul_f32 v[214:215], v[58:59], v[186:187]
	v_pk_mul_f32 v[214:215], v[214:215], v[198:199] op_sel_hi:[1,0]
	v_cvt_pk_bf16_f32 v221, v214, v215
	global_store_short v206, v221, s[4:5] offset:64
	global_store_short_d16_hi v207, v221, s[4:5] offset:64
	v_pk_mul_f32 v[212:213], v[60:61], v[192:193]
	v_pk_mul_f32 v[212:213], v[212:213], v[198:199] op_sel_hi:[1,0]
	v_cvt_pk_bf16_f32 v222, v212, v213
	global_store_short v208, v222, s[4:5] offset:64
	global_store_short_d16_hi v209, v222, s[4:5] offset:64
	v_pk_mul_f32 v[214:215], v[62:63], v[194:195]
	v_pk_mul_f32 v[214:215], v[214:215], v[198:199] op_sel_hi:[1,0]
	v_cvt_pk_bf16_f32 v223, v214, v215
	global_store_short v210, v223, s[4:5] offset:64
	global_store_short_d16_hi v211, v223, s[4:5] offset:64
	v_pk_mul_f32 v[212:213], v[32:33], v[176:177]
	v_pk_mul_f32 v[212:213], v[212:213], v[200:201] op_sel_hi:[1,0]
	v_cvt_pk_bf16_f32 v216, v212, v213
	global_store_short v204, v216, s[0:1] offset:128
	global_store_short_d16_hi v205, v216, s[0:1] offset:128
	v_pk_mul_f32 v[214:215], v[34:35], v[178:179]
	v_pk_mul_f32 v[214:215], v[214:215], v[200:201] op_sel_hi:[1,0]
	v_cvt_pk_bf16_f32 v217, v214, v215
	global_store_short v206, v217, s[0:1] offset:128
	global_store_short_d16_hi v207, v217, s[0:1] offset:128
	v_pk_mul_f32 v[212:213], v[36:37], v[180:181]
	v_pk_mul_f32 v[212:213], v[212:213], v[200:201] op_sel_hi:[1,0]
	v_cvt_pk_bf16_f32 v218, v212, v213
	global_store_short v208, v218, s[0:1] offset:128
	global_store_short_d16_hi v209, v218, s[0:1] offset:128
	v_pk_mul_f32 v[214:215], v[38:39], v[182:183]
	v_pk_mul_f32 v[214:215], v[214:215], v[200:201] op_sel_hi:[1,0]
	v_cvt_pk_bf16_f32 v219, v214, v215
	global_store_short v210, v219, s[0:1] offset:128
	global_store_short_d16_hi v211, v219, s[0:1] offset:128
	v_pk_mul_f32 v[212:213], v[40:41], v[184:185]
	v_pk_mul_f32 v[212:213], v[212:213], v[200:201] op_sel_hi:[1,0]
	v_cvt_pk_bf16_f32 v220, v212, v213
	global_store_short v204, v220, s[4:5] offset:128
	global_store_short_d16_hi v205, v220, s[4:5] offset:128
	v_pk_mul_f32 v[214:215], v[42:43], v[186:187]
	v_pk_mul_f32 v[214:215], v[214:215], v[200:201] op_sel_hi:[1,0]
	v_cvt_pk_bf16_f32 v221, v214, v215
	global_store_short v206, v221, s[4:5] offset:128
	global_store_short_d16_hi v207, v221, s[4:5] offset:128
	v_pk_mul_f32 v[212:213], v[44:45], v[192:193]
	v_pk_mul_f32 v[212:213], v[212:213], v[200:201] op_sel_hi:[1,0]
	v_cvt_pk_bf16_f32 v222, v212, v213
	global_store_short v208, v222, s[4:5] offset:128
	global_store_short_d16_hi v209, v222, s[4:5] offset:128
	v_pk_mul_f32 v[214:215], v[46:47], v[194:195]
	v_pk_mul_f32 v[214:215], v[214:215], v[200:201] op_sel_hi:[1,0]
	v_cvt_pk_bf16_f32 v223, v214, v215
	global_store_short v210, v223, s[4:5] offset:128
	global_store_short_d16_hi v211, v223, s[4:5] offset:128
	v_pk_mul_f32 v[212:213], v[16:17], v[176:177]
	v_pk_mul_f32 v[212:213], v[212:213], v[202:203] op_sel_hi:[1,0]
	v_cvt_pk_bf16_f32 v216, v212, v213
	global_store_short v204, v216, s[0:1] offset:192
	global_store_short_d16_hi v205, v216, s[0:1] offset:192
	v_pk_mul_f32 v[214:215], v[18:19], v[178:179]
	v_pk_mul_f32 v[214:215], v[214:215], v[202:203] op_sel_hi:[1,0]
	v_cvt_pk_bf16_f32 v217, v214, v215
	global_store_short v206, v217, s[0:1] offset:192
	global_store_short_d16_hi v207, v217, s[0:1] offset:192
	v_pk_mul_f32 v[212:213], v[20:21], v[180:181]
	v_pk_mul_f32 v[212:213], v[212:213], v[202:203] op_sel_hi:[1,0]
	v_cvt_pk_bf16_f32 v218, v212, v213
	global_store_short v208, v218, s[0:1] offset:192
	global_store_short_d16_hi v209, v218, s[0:1] offset:192
	v_pk_mul_f32 v[214:215], v[22:23], v[182:183]
	v_pk_mul_f32 v[214:215], v[214:215], v[202:203] op_sel_hi:[1,0]
	v_cvt_pk_bf16_f32 v219, v214, v215
	global_store_short v210, v219, s[0:1] offset:192
	global_store_short_d16_hi v211, v219, s[0:1] offset:192
	v_pk_mul_f32 v[212:213], v[24:25], v[184:185]
	v_pk_mul_f32 v[212:213], v[212:213], v[202:203] op_sel_hi:[1,0]
	v_cvt_pk_bf16_f32 v220, v212, v213
	global_store_short v204, v220, s[4:5] offset:192
	global_store_short_d16_hi v205, v220, s[4:5] offset:192
	v_pk_mul_f32 v[214:215], v[26:27], v[186:187]
	v_pk_mul_f32 v[214:215], v[214:215], v[202:203] op_sel_hi:[1,0]
	v_cvt_pk_bf16_f32 v221, v214, v215
	global_store_short v206, v221, s[4:5] offset:192
	global_store_short_d16_hi v207, v221, s[4:5] offset:192
	v_pk_mul_f32 v[212:213], v[28:29], v[192:193]
	v_pk_mul_f32 v[212:213], v[212:213], v[202:203] op_sel_hi:[1,0]
	v_cvt_pk_bf16_f32 v222, v212, v213
	global_store_short v208, v222, s[4:5] offset:192
	global_store_short_d16_hi v209, v222, s[4:5] offset:192
	v_pk_mul_f32 v[214:215], v[30:31], v[194:195]
	v_pk_mul_f32 v[214:215], v[214:215], v[202:203] op_sel_hi:[1,0]
	v_cvt_pk_bf16_f32 v223, v214, v215
	global_store_short v210, v223, s[4:5] offset:192
	global_store_short_d16_hi v211, v223, s[4:5] offset:192
	s_waitcnt vmcnt(0)
	s_barrier
	s_add_i32 s16, s16, s30
	s_cmpk_lt_i32 s16, 0x400
	s_cbranch_scc1 .LBB0_316

; __global__ void __launch_bounds__(512) fwd_megakernel(Params p) {
	.amdhsa_kernel _Z14fwd_megakernel6Params
		.amdhsa_group_segment_fixed_size 0
		.amdhsa_private_segment_fixed_size 0
		.amdhsa_kernarg_size 456
		.amdhsa_user_sgpr_count 2
		.amdhsa_user_sgpr_dispatch_ptr 0
		.amdhsa_user_sgpr_queue_ptr 0
		.amdhsa_user_sgpr_kernarg_segment_ptr 1
		.amdhsa_user_sgpr_dispatch_id 0
		.amdhsa_user_sgpr_kernarg_preload_length 0
		.amdhsa_user_sgpr_kernarg_preload_offset 0
		.amdhsa_user_sgpr_private_segment_size 0
		.amdhsa_uses_dynamic_stack 0
		.amdhsa_enable_private_segment 0
		.amdhsa_system_sgpr_workgroup_id_x 1
		.amdhsa_system_sgpr_workgroup_id_y 0
		.amdhsa_system_sgpr_workgroup_id_z 0
		.amdhsa_system_sgpr_workgroup_info 0
		.amdhsa_system_vgpr_workitem_id 2
		.amdhsa_next_free_vgpr 246
		.amdhsa_next_free_sgpr 102
		.amdhsa_accum_offset 248
		.amdhsa_reserve_vcc 1
		.amdhsa_float_round_mode_32 0
		.amdhsa_float_round_mode_16_64 0
		.amdhsa_float_denorm_mode_32 3
		.amdhsa_float_denorm_mode_16_64 3
		.amdhsa_dx10_clamp 1
		.amdhsa_ieee_mode 1
		.amdhsa_fp16_overflow 0
		.amdhsa_tg_split 0
		.amdhsa_exception_fp_ieee_invalid_op 0
		.amdhsa_exception_fp_denorm_src 0
		.amdhsa_exception_fp_ieee_div_zero 0
		.amdhsa_exception_fp_ieee_overflow 0
		.amdhsa_exception_fp_ieee_underflow 0
		.amdhsa_exception_fp_ieee_inexact 0
		.amdhsa_exception_int_div_zero 0
	.end_amdhsa_kernel

; __global__ void __launch_bounds__(512) fwd_megakernel(Params p) {
amdhsa.kernels:
  - .agpr_count:     0
    .args:
      - .offset:         0
        .size:           200
        .value_kind:     by_value
      - .offset:         200
        .size:           4
        .value_kind:     hidden_block_count_x
      - .offset:         204
        .size:           4
        .value_kind:     hidden_block_count_y
      - .offset:         208
        .size:           4
        .value_kind:     hidden_block_count_z
      - .offset:         212
        .size:           2
        .value_kind:     hidden_group_size_x
      - .offset:         214
        .size:           2
        .value_kind:     hidden_group_size_y
      - .offset:         216
        .size:           2
        .value_kind:     hidden_group_size_z
      - .offset:         218
        .size:           2
        .value_kind:     hidden_remainder_x
      - .offset:         220
        .size:           2
        .value_kind:     hidden_remainder_y
      - .offset:         222
        .size:           2
        .value_kind:     hidden_remainder_z
      - .offset:         240
        .size:           8
        .value_kind:     hidden_global_offset_x
      - .offset:         248
        .size:           8
        .value_kind:     hidden_global_offset_y
      - .offset:         256
        .size:           8
        .value_kind:     hidden_global_offset_z
      - .offset:         264
        .size:           2
        .value_kind:     hidden_grid_dims
      - .offset:         288
        .size:           8
        .value_kind:     hidden_multigrid_sync_arg
      - .offset:         320
        .size:           4
        .value_kind:     hidden_dynamic_lds_size
    .group_segment_fixed_size: 0
    .kernarg_segment_align: 8
    .kernarg_segment_size: 456
    .language:       OpenCL C
    .language_version:
      - 2
      - 0
    .max_flat_workgroup_size: 512
    .name:           _Z14fwd_megakernel6Params
    .private_segment_fixed_size: 0
    .sgpr_count:     108
    .sgpr_spill_count: 31
    .symbol:         _Z14fwd_megakernel6Params.kd
    .uniform_work_group_size: 1
    .uses_dynamic_stack: false
    .vgpr_count:     246
    .vgpr_spill_count: 0
    .wavefront_size: 64
